# B loop: SIMD partner waves run different orders inside a tile (waves 0-3: A weights, B weights, one merged P.V burst reading V once; waves 4-7: A weights, P_A.V, B weights, P_B.V) so one partner's mat
# speedup vs baseline: 1.0034x; 1.0034x over previous
; #define LAS __attribute__((address_space(3)))
; DI float fexp2(float x) { return __builtin_amdgcn_exp2f(x); }
; DI int vbyte(int key, int chunk) { return (chunk >> 2) * 4096 + (key >> 4) * 1024 + (key & 15) * 64 + (chunk & 3) * 16; }
; DI float max2f(float a, float b) { float r; asm("v_max_f32_e32 %0, %1, %2" : "=v"(r) : "v"(a), "v"(b)); return r; }
; DI float xhalf_max(float v) { auto rr = __builtin_amdgcn_permlane32_swap(__float_as_uint(v), __float_as_uint(v), false, false); return max2f(__uint_as_float(rr[0]), __uint_as_float(rr[1])); }
; DI void attn_diff_unit(int ub, int Ssh, float lam, float post, const float* subg, const bf16_t* PROJ, bf16_t* O, LAS unsigned char* lds, int wid, int lane) {
;     ...
;     const bf16_t* ksrc = Kb + (size_t)(8 * wid + (lane >> 3)) * PQ + 8 * (lane & 7);
;     const bf16_t* vsrc = Vb + (size_t)(8 * wid + (lane >> 3)) * PQ + 8 * (lane & 7);
;     const int kdst = kbyte(8 * wid + (lane >> 3), lane & 7), vdst = 8192 + vbyte(8 * wid + (lane >> 3), lane & 7);
;     const int NT = S >> 6;
;     float mA = 0.f, mB = 0.f, lA = 0.f, lB = 0.f; f32x16 a0 = zero16(), a1 = zero16(), b0 = zero16(), b1 = zero16();
;     u32x4 kA = *(const u32x4*)ksrc, vA = *(const u32x4*)vsrc;
;     *(LAS u32x4*)(lds + kdst) = kA; *(LAS u32x4*)(lds + vdst) = vA;
;     __syncthreads();
;     const int vlane = ((lane >> 4) & 1) * 32 + (lane & 3) * 8 + (4 * hi + ((lane & 15) >> 2)) * 64;
;     auto tile = [&](const int t, LAS unsigned char* cur) {
;         f32x16 pa0, pa1, pb0, pb1; u32x4 pwA[4], pwB[4];
;         qk64<2, 0>(pa0, pa1, cur, qr, r32, hi);
;         qk64<2, 2>(pb0, pb1, cur, qr, r32, hi);
;         const float mxA = xhalf_max(rowmax32(pa0, pa1)), mxB = xhalf_max(rowmax32(pb0, pb1));
;         if (t == 0 || __any(mxA > mA + 8.0f || mxB > mB + 8.0f)) {
;             const float nA = (t == 0) ? mxA : max2f(mA, mxA), nB = (t == 0) ? mxB : max2f(mB, mxB);
;             const float fA = fexp2(mA - nA), fB = fexp2(mB - nB); mA = nA; mB = nB; lA *= fA; lB *= fB;
.Lbt_entry:
	v_add3_u32 v168, v213, v212, v211
	v_add3_u32 v169, v215, v214, v211
	v_add3_u32 v200, v217, v216, v211
	v_add3_u32 v201, v219, v218, v211
	v_add3_u32 v224, v207, v208, v209
	v_add_u32_e32 v224, v224, v210
	v_or_b32_e32 v168, 0x4000, v168
	v_or_b32_e32 v169, 0x4000, v169
	v_or_b32_e32 v200, 0x4000, v200
	v_or_b32_e32 v201, 0x4000, v201
	v_or_b32_e32 v224, 0x4000, v224
	v_sub_f32_e32 v176, 0, v220
	v_mov_b32_e32 v177, v176
	v_mov_b32_e32 v178, v176
	v_mov_b32_e32 v179, v176
	v_mov_b32_e32 v180, v176
	v_mov_b32_e32 v181, v176
	v_mov_b32_e32 v182, v176
	v_mov_b32_e32 v183, v176
	v_mov_b32_e32 v184, v176
	v_mov_b32_e32 v185, v176
	v_mov_b32_e32 v186, v176
	v_mov_b32_e32 v187, v176
	v_mov_b32_e32 v188, v176
	v_mov_b32_e32 v189, v176
	v_mov_b32_e32 v190, v176
	v_mov_b32_e32 v191, v176
	v_sub_f32_e32 v0, 0, v221
	v_mov_b32_e32 v208, v0
	v_mov_b32_e32 v209, v0
	v_mov_b32_e32 v210, v0
	v_mov_b32_e32 v211, v0
	v_mov_b32_e32 v212, v0
	v_mov_b32_e32 v213, v0
	v_mov_b32_e32 v214, v0
	v_mov_b32_e32 v215, v0
	v_mov_b32_e32 v216, v0
	v_mov_b32_e32 v217, v0
	v_mov_b32_e32 v218, v0
	v_mov_b32_e32 v219, v0
	v_mov_b32_e32 v220, v0
	v_mov_b32_e32 v221, v0
	v_mov_b32_e32 v222, v0
	v_mov_b32_e32 v223, v0
	v_mul_f32_e32 v156, 0.5, v156
	v_mul_f32_e32 v157, 0.5, v157
	v_mov_b32_e32 v226, 0x3f803f80
	v_mov_b32_e32 v227, 0x3f803f80
	s_cmp_ge_u32 s13, 32
	s_cbranch_scc1 .Lbt_loop_y

; #define LAS __attribute__((address_space(3)))
; DI void attn_diff_unit(int ub, int Ssh, float lam, float post, const float* subg, const bf16_t* PROJ, bf16_t* O, LAS unsigned char* lds, int wid, int lane) {
;     ...
;     for (int t = 0; t < NT; ++t) {
;         LAS unsigned char* cur = lds + (t & 1) * 16384; LAS unsigned char* nxt = lds + ((t + 1) & 1) * 16384;
;         if (t + 1 < NT) { kA = *(const u32x4*)(ksrc + (size_t)(t + 1) * 64 * PQ); vA = *(const u32x4*)(vsrc + (size_t)(t + 1) * 64 * PQ); }
;         tile(t, cur);
;         if (t + 1 < NT) { *(LAS u32x4*)(nxt + kdst) = kA; *(LAS u32x4*)(nxt + vdst) = vA; }
;         __syncthreads();
;     }
.Lbt_nowr_x:
	v_xor_b32_e32 v205, 0x4000, v205
	v_xor_b32_e32 v206, 0x4000, v206
	v_xor_b32_e32 v224, 0x4000, v224
	s_mov_b64 s[0:1], 0x62000
	v_lshl_add_u64 v[158:159], v[158:159], 0, s[0:1]
	s_cmp_lg_u32 s39, s10
	s_waitcnt lgkmcnt(0)
	s_barrier
	s_cbranch_scc1 .Lbt_loop_x
	s_branch .Lbt_exit

; #define LAS __attribute__((address_space(3)))
; DI void attn_diff_unit(int ub, int Ssh, float lam, float post, const float* subg, const bf16_t* PROJ, bf16_t* O, LAS unsigned char* lds, int wid, int lane) {
;     ...
;         float sA = 0.f, sB = 0.f;
; #pragma unroll
;         for (int r = 0; r < 16; ++r) { pa0[r] = fexp2(pa0[r] - mA); pa1[r] = fexp2(pa1[r] - mA); sA += pa0[r] + pa1[r]; }
;         pwA[0] = (u32x4){cvtpk(pa0[0], pa0[1]), cvtpk(pa0[2], pa0[3]), cvtpk(pa0[4], pa0[5]), cvtpk(pa0[6], pa0[7])};
;         pwA[1] = (u32x4){cvtpk(pa0[8], pa0[9]), cvtpk(pa0[10], pa0[11]), cvtpk(pa0[12], pa0[13]), cvtpk(pa0[14], pa0[15])};
;         pwA[2] = (u32x4){cvtpk(pa1[0], pa1[1]), cvtpk(pa1[2], pa1[3]), cvtpk(pa1[4], pa1[5]), cvtpk(pa1[6], pa1[7])};
;         pwA[3] = (u32x4){cvtpk(pa1[8], pa1[9]), cvtpk(pa1[10], pa1[11]), cvtpk(pa1[12], pa1[13]), cvtpk(pa1[14], pa1[15])};
;         LAS const unsigned char* vp = cur + 8192 + vlane;
; #pragma unroll
;         for (int ks = 0; ks < 4; ++ks) {
;             const s16x4 lo0 = vtr(vp + ks * 1024), hi0 = vtr(vp + ks * 1024 + 512), lo1 = vtr(vp + 4096 + ks * 1024), hi1 = vtr(vp + 4096 + ks * 1024 + 512);
;             const bf16x8 v0 = (bf16x8){lo0[0], lo0[1], lo0[2], lo0[3], hi0[0], hi0[1], hi0[2], hi0[3]};
;             const bf16x8 v1 = (bf16x8){lo1[0], lo1[1], lo1[2], lo1[3], hi1[0], hi1[1], hi1[2], hi1[3]};
;             const bf16x8 pa = __builtin_bit_cast(bf16x8, pwA[ks]);
;             a0 = __builtin_amdgcn_mfma_f32_32x32x16_bf16(v0, pa, a0, 0, 0, 0);
;             a1 = __builtin_amdgcn_mfma_f32_32x32x16_bf16(v1, pa, a1, 0, 0, 0);
; #pragma unroll
;             for (int r = 4 * ks; r < 4 * ks + 4; ++r) { pb0[r] = fexp2(pb0[r] - mB); pb1[r] = fexp2(pb1[r] - mB); sB += pb0[r] + pb1[r]; }
;         }
;         lA += xhalf_sum(sA); lB += xhalf_sum(sB);
;         pwB[0] = (u32x4){cvtpk(pb0[0], pb0[1]), cvtpk(pb0[2], pb0[3]), cvtpk(pb0[4], pb0[5]), cvtpk(pb0[6], pb0[7])};
;         pwB[1] = (u32x4){cvtpk(pb0[8], pb0[9]), cvtpk(pb0[10], pb0[11]), cvtpk(pb0[12], pb0[13]), cvtpk(pb0[14], pb0[15])};
;         pwB[2] = (u32x4){cvtpk(pb1[0], pb1[1]), cvtpk(pb1[2], pb1[3]), cvtpk(pb1[4], pb1[5]), cvtpk(pb1[6], pb1[7])};
;         pwB[3] = (u32x4){cvtpk(pb1[8], pb1[9]), cvtpk(pb1[10], pb1[11]), cvtpk(pb1[12], pb1[13]), cvtpk(pb1[14], pb1[15])};
; #pragma unroll
;         for (int ks = 0; ks < 4; ++ks) {
.Lbt_ok_a_y:
	v_add_f32_e32 v156, v156, v196
	s_barrier
	s_waitcnt lgkmcnt(0)
	v_mfma_f32_32x32x16_bf16 v[34:49], v[74:77], v[66:69], v[34:49]
	v_mfma_f32_32x32x16_bf16 v[2:17], v[78:81], v[66:69], v[2:17]
	ds_read_b64_tr_b16 v[74:75], v224 offset:10240
	ds_read_b64_tr_b16 v[76:77], v224 offset:10752
	ds_read_b64_tr_b16 v[78:79], v224 offset:14336
	ds_read_b64_tr_b16 v[80:81], v224 offset:14848
	v_mfma_f32_32x32x16_bf16 v[34:49], v[90:93], v[70:73], v[34:49]
	v_mfma_f32_32x32x16_bf16 v[2:17], v[94:97], v[70:73], v[2:17]
	ds_read_b64_tr_b16 v[90:91], v224 offset:11264
	ds_read_b64_tr_b16 v[92:93], v224 offset:11776
	ds_read_b64_tr_b16 v[94:95], v224 offset:15360
	ds_read_b64_tr_b16 v[96:97], v224 offset:15872
	s_waitcnt lgkmcnt(4)
	v_mfma_f32_32x32x16_bf16 v[34:49], v[74:77], v[82:85], v[34:49]
	v_mfma_f32_32x32x16_bf16 v[2:17], v[78:81], v[82:85], v[2:17]
	ds_read_b64_tr_b16 v[74:75], v224 offset:8192
	ds_read_b64_tr_b16 v[76:77], v224 offset:8704
	ds_read_b64_tr_b16 v[78:79], v224 offset:12288
	ds_read_b64_tr_b16 v[80:81], v224 offset:12800
	s_waitcnt lgkmcnt(4)
	v_mfma_f32_32x32x16_bf16 v[34:49], v[90:93], v[86:89], v[34:49]
	v_mfma_f32_32x32x16_bf16 v[2:17], v[94:97], v[86:89], v[2:17]
	ds_read_b64_tr_b16 v[90:91], v224 offset:9216
	ds_read_b64_tr_b16 v[92:93], v224 offset:9728
	ds_read_b64_tr_b16 v[94:95], v224 offset:13312
	ds_read_b64_tr_b16 v[96:97], v224 offset:13824
	v_exp_f32_e32 v98, v98
	v_exp_f32_e32 v99, v99
	v_exp_f32_e32 v100, v100
	v_exp_f32_e32 v101, v101
	v_exp_f32_e32 v102, v102
	v_exp_f32_e32 v103, v103
	v_mov_b32_e32 v192, v98
	v_mov_b32_e32 v193, v99
	v_cvt_pk_bf16_f32 v98, v98, v99
	v_exp_f32_e32 v104, v104
	v_exp_f32_e32 v105, v105
	v_add_f32_e32 v192, v192, v100
	v_add_f32_e32 v193, v193, v101
	v_cvt_pk_bf16_f32 v99, v100, v101
	v_exp_f32_e32 v106, v106
	v_exp_f32_e32 v107, v107
	v_add_f32_e32 v192, v192, v102
	v_add_f32_e32 v193, v193, v103
	v_cvt_pk_bf16_f32 v100, v102, v103
	v_exp_f32_e32 v108, v108
	v_exp_f32_e32 v109, v109
	v_add_f32_e32 v192, v192, v104
	v_add_f32_e32 v193, v193, v105
	v_cvt_pk_bf16_f32 v101, v104, v105
	v_exp_f32_e32 v110, v110
	v_exp_f32_e32 v111, v111
	v_add_f32_e32 v192, v192, v106
	v_add_f32_e32 v193, v193, v107
	v_cvt_pk_bf16_f32 v102, v106, v107
	v_exp_f32_e32 v112, v112
	v_exp_f32_e32 v113, v113
	v_add_f32_e32 v192, v192, v108
	v_add_f32_e32 v193, v193, v109
	v_cvt_pk_bf16_f32 v103, v108, v109
	v_add_f32_e32 v192, v192, v110
	v_add_f32_e32 v193, v193, v111
	v_cvt_pk_bf16_f32 v104, v110, v111
	v_add_f32_e32 v192, v192, v112
	v_add_f32_e32 v193, v193, v113
	v_cvt_pk_bf16_f32 v105, v112, v113
	v_exp_f32_e32 v114, v114
	v_exp_f32_e32 v115, v115
	v_exp_f32_e32 v116, v116
	v_exp_f32_e32 v117, v117
	v_exp_f32_e32 v118, v118
	v_exp_f32_e32 v119, v119
	v_add_f32_e32 v192, v192, v114
	v_add_f32_e32 v193, v193, v115
	v_cvt_pk_bf16_f32 v114, v114, v115
	v_exp_f32_e32 v120, v120
	v_exp_f32_e32 v121, v121
	v_add_f32_e32 v192, v192, v116
	v_add_f32_e32 v193, v193, v117
	v_cvt_pk_bf16_f32 v115, v116, v117
	v_exp_f32_e32 v122, v122
	v_exp_f32_e32 v123, v123
	v_add_f32_e32 v192, v192, v118
	v_add_f32_e32 v193, v193, v119
	v_cvt_pk_bf16_f32 v116, v118, v119
	v_exp_f32_e32 v124, v124
	v_exp_f32_e32 v125, v125
	v_add_f32_e32 v192, v192, v120
	v_add_f32_e32 v193, v193, v121
	v_cvt_pk_bf16_f32 v117, v120, v121
	v_exp_f32_e32 v126, v126
	v_exp_f32_e32 v127, v127
	v_add_f32_e32 v192, v192, v122
	v_add_f32_e32 v193, v193, v123
	v_cvt_pk_bf16_f32 v118, v122, v123
	v_exp_f32_e32 v128, v128
	v_exp_f32_e32 v129, v129
	v_add_f32_e32 v192, v192, v124
	v_add_f32_e32 v193, v193, v125
	v_cvt_pk_bf16_f32 v119, v124, v125
	v_add_f32_e32 v192, v192, v126
	v_add_f32_e32 v193, v193, v127
	v_cvt_pk_bf16_f32 v120, v126, v127
	v_add_f32_e32 v192, v192, v128
	v_add_f32_e32 v193, v193, v129
	v_cvt_pk_bf16_f32 v121, v128, v129
	v_add_f32_e32 v192, v192, v193
	v_cmp_ngt_f32_e32 vcc, 0x5d800000, v192
	s_cbranch_vccnz .Lbt_redo_b_y
.Lbt_ok_b_y:
	v_add_f32_e32 v157, v157, v192
	s_waitcnt lgkmcnt(0)
	v_mfma_f32_32x32x16_bf16 v[50:65], v[74:77], v[98:101], v[50:65]
	v_mfma_f32_32x32x16_bf16 v[18:33], v[78:81], v[98:101], v[18:33]
	ds_read_b64_tr_b16 v[74:75], v224 offset:10240
	ds_read_b64_tr_b16 v[76:77], v224 offset:10752
	ds_read_b64_tr_b16 v[78:79], v224 offset:14336
	ds_read_b64_tr_b16 v[80:81], v224 offset:14848
	v_mfma_f32_32x32x16_bf16 v[50:65], v[90:93], v[102:105], v[50:65]
	v_mfma_f32_32x32x16_bf16 v[18:33], v[94:97], v[102:105], v[18:33]
	ds_read_b64_tr_b16 v[90:91], v224 offset:11264
	ds_read_b64_tr_b16 v[92:93], v224 offset:11776
	ds_read_b64_tr_b16 v[94:95], v224 offset:15360
	ds_read_b64_tr_b16 v[96:97], v224 offset:15872
	s_waitcnt lgkmcnt(4)
	v_mfma_f32_32x32x16_bf16 v[50:65], v[74:77], v[114:117], v[50:65]
	v_mfma_f32_32x32x16_bf16 v[18:33], v[78:81], v[114:117], v[18:33]
	s_waitcnt lgkmcnt(0)
	v_mfma_f32_32x32x16_bf16 v[50:65], v[90:93], v[118:121], v[50:65]
	v_mfma_f32_32x32x16_bf16 v[18:33], v[94:97], v[118:121], v[18:33]
	s_andn2_b64 vcc, exec, s[2:3]
	s_cbranch_vccnz .Lbt_nowr_y
	s_waitcnt vmcnt(1)
	ds_write_b128 v205, v[146:149]
	s_waitcnt vmcnt(0)
	ds_write_b128 v206, v[150:153] offset:8192

; DI float xhalf_sum(float v) { auto rr = __builtin_amdgcn_permlane32_swap(__float_as_uint(v), __float_as_uint(v), false, false); return __uint_as_float(rr[0]) + __uint_as_float(rr[1]); }
; DI void attn_diff_unit(int ub, int Ssh, float lam, float post, const float* subg, const bf16_t* PROJ, bf16_t* O, LAS unsigned char* lds, int wid, int lane) {
;     ...
;         lA += xhalf_sum(sA); lB += xhalf_sum(sB);
.Lbt_exit:
	v_mov_b32_e32 v196, v156
	v_mov_b32_e32 v192, v157
	s_nop 1
	v_permlane32_swap_b32_e32 v156, v196
	v_permlane32_swap_b32_e32 v157, v192
	v_add_f32_e32 v156, v156, v196
	v_add_f32_e32 v157, v157, v192
	s_branch .LBB0_514

; #define LAS __attribute__((address_space(3)))
; DI void attn_diff_unit(int ub, int Ssh, float lam, float post, const float* subg, const bf16_t* PROJ, bf16_t* O, LAS unsigned char* lds, int wid, int lane) {
;     ...
;         qk64<2, 2>(pb0, pb1, cur, qr, r32, hi);
;         const float mxA = xhalf_max(rowmax32(pa0, pa1)), mxB = xhalf_max(rowmax32(pb0, pb1));
;         if (t == 0 || __any(mxA > mA + 8.0f || mxB > mB + 8.0f)) {
;             const float nA = (t == 0) ? mxA : max2f(mA, mxA), nB = (t == 0) ? mxB : max2f(mB, mxB);
;             const float fA = fexp2(mA - nA), fB = fexp2(mB - nB); mA = nA; mB = nB; lA *= fA; lB *= fB;
; #pragma unroll
;             for (int r = 0; r < 16; ++r) { a0[r] *= fA; a1[r] *= fA; b0[r] *= fB; b1[r] *= fB; }
;         }
;         float sA = 0.f, sB = 0.f;
; #pragma unroll
;         for (int r = 0; r < 16; ++r) { pa0[r] = fexp2(pa0[r] - mA); pa1[r] = fexp2(pa1[r] - mA); sA += pa0[r] + pa1[r]; }
;         pwA[0] = (u32x4){cvtpk(pa0[0], pa0[1]), cvtpk(pa0[2], pa0[3]), cvtpk(pa0[4], pa0[5]), cvtpk(pa0[6], pa0[7])};
;         pwA[1] = (u32x4){cvtpk(pa0[8], pa0[9]), cvtpk(pa0[10], pa0[11]), cvtpk(pa0[12], pa0[13]), cvtpk(pa0[14], pa0[15])};
;         pwA[2] = (u32x4){cvtpk(pa1[0], pa1[1]), cvtpk(pa1[2], pa1[3]), cvtpk(pa1[4], pa1[5]), cvtpk(pa1[6], pa1[7])};
;         pwA[3] = (u32x4){cvtpk(pa1[8], pa1[9]), cvtpk(pa1[10], pa1[11]), cvtpk(pa1[12], pa1[13]), cvtpk(pa1[14], pa1[15])};
;         LAS const unsigned char* vp = cur + 8192 + vlane;
; #pragma unroll
;         for (int ks = 0; ks < 4; ++ks) {
;             const s16x4 lo0 = vtr(vp + ks * 1024), hi0 = vtr(vp + ks * 1024 + 512), lo1 = vtr(vp + 4096 + ks * 1024), hi1 = vtr(vp + 4096 + ks * 1024 + 512);
;             const bf16x8 v0 = (bf16x8){lo0[0], lo0[1], lo0[2], lo0[3], hi0[0], hi0[1], hi0[2], hi0[3]};
;             const bf16x8 v1 = (bf16x8){lo1[0], lo1[1], lo1[2], lo1[3], hi1[0], hi1[1], hi1[2], hi1[3]};
;             const bf16x8 pa = __builtin_bit_cast(bf16x8, pwA[ks]);
;             a0 = __builtin_amdgcn_mfma_f32_32x32x16_bf16(v0, pa, a0, 0, 0, 0);
;             a1 = __builtin_amdgcn_mfma_f32_32x32x16_bf16(v1, pa, a1, 0, 0, 0);
; #pragma unroll
;             for (int r = 4 * ks; r < 4 * ks + 4; ++r) { pb0[r] = fexp2(pb0[r] - mB); pb1[r] = fexp2(pb1[r] - mB); sB += pb0[r] + pb1[r]; }
;         }
;         lA += xhalf_sum(sA); lB += xhalf_sum(sB);
.Lbt_redo_b_x:
	v_xor_b32_e32 v0, 0x4000, v200
	v_xor_b32_e32 v207, 0x4000, v201
	ds_read_b128 v[114:117], v0
	ds_read_b128 v[118:121], v207
	ds_read_b128 v[160:163], v0 offset:512
	ds_read_b128 v[164:167], v207 offset:512
	s_waitcnt lgkmcnt(0)
	v_mfma_f32_32x32x16_bf16 v[98:113], v[114:117], v[138:141], v[208:223]
	v_mfma_f32_32x32x16_bf16 v[98:113], v[118:121], v[142:145], v[98:113]
	v_mfma_f32_32x32x16_bf16 v[114:129], v[160:163], v[138:141], v[208:223]
	v_mfma_f32_32x32x16_bf16 v[114:129], v[164:167], v[142:145], v[114:129]
	s_nop 7
	s_nop 7
	v_max3_f32 v192, v98, v99, v100
	v_max3_f32 v193, v101, v102, v103
	v_max3_f32 v192, v192, v104, v105
	v_max3_f32 v193, v193, v106, v107
	v_max3_f32 v192, v192, v108, v109
	v_max3_f32 v193, v193, v110, v111
	v_max3_f32 v192, v192, v112, v113
	v_max3_f32 v193, v193, v114, v115
	v_max3_f32 v192, v192, v116, v117
	v_max3_f32 v193, v193, v118, v119
	v_max3_f32 v192, v192, v120, v121
	v_max3_f32 v193, v193, v122, v123
	v_max3_f32 v192, v192, v124, v125
	v_max3_f32 v193, v193, v126, v127
	v_max3_f32 v192, v192, v128, v129
	v_max_f32_e32 v192, v192, v193
	v_mov_b32_e32 v193, v192
	s_nop 1
	v_permlane32_swap_b32_e32 v192, v193
	v_max_f32_e32 v192, v192, v193
	v_max_f32_e32 v192, 0, v192
	v_exp_f32_e64 v193, -v192
	v_sub_f32_e32 v208, v208, v192
	v_sub_f32_e32 v209, v209, v192
	v_sub_f32_e32 v210, v210, v192
	v_sub_f32_e32 v211, v211, v192
	v_sub_f32_e32 v212, v212, v192
	v_sub_f32_e32 v213, v213, v192
	v_sub_f32_e32 v214, v214, v192
	v_sub_f32_e32 v215, v215, v192
	v_sub_f32_e32 v216, v216, v192
	v_sub_f32_e32 v217, v217, v192
	v_sub_f32_e32 v218, v218, v192
	v_sub_f32_e32 v219, v219, v192
	v_sub_f32_e32 v220, v220, v192
	v_sub_f32_e32 v221, v221, v192
	v_sub_f32_e32 v222, v222, v192
	v_sub_f32_e32 v223, v223, v192
	v_sub_f32_e32 v98, v98, v192
	v_sub_f32_e32 v99, v99, v192
	v_sub_f32_e32 v100, v100, v192
	v_sub_f32_e32 v101, v101, v192
	v_sub_f32_e32 v102, v102, v192
	v_sub_f32_e32 v103, v103, v192
	v_sub_f32_e32 v104, v104, v192
	v_sub_f32_e32 v105, v105, v192
	v_sub_f32_e32 v106, v106, v192
	v_sub_f32_e32 v107, v107, v192
	v_sub_f32_e32 v108, v108, v192
	v_sub_f32_e32 v109, v109, v192
	v_sub_f32_e32 v110, v110, v192
	v_sub_f32_e32 v111, v111, v192
	v_sub_f32_e32 v112, v112, v192
	v_sub_f32_e32 v113, v113, v192
	v_sub_f32_e32 v114, v114, v192
	v_sub_f32_e32 v115, v115, v192
	v_sub_f32_e32 v116, v116, v192
	v_sub_f32_e32 v117, v117, v192
	v_sub_f32_e32 v118, v118, v192
	v_sub_f32_e32 v119, v119, v192
	v_sub_f32_e32 v120, v120, v192
	v_sub_f32_e32 v121, v121, v192
	v_sub_f32_e32 v122, v122, v192
	v_sub_f32_e32 v123, v123, v192
	v_sub_f32_e32 v124, v124, v192
	v_sub_f32_e32 v125, v125, v192
	v_sub_f32_e32 v126, v126, v192
	v_sub_f32_e32 v127, v127, v192
	v_sub_f32_e32 v128, v128, v192
	v_sub_f32_e32 v129, v129, v192
	v_mul_f32_e32 v157, v157, v193
	v_mul_f32_e32 v50, v50, v193
	v_mul_f32_e32 v51, v51, v193
	v_mul_f32_e32 v52, v52, v193
	v_mul_f32_e32 v53, v53, v193
	v_mul_f32_e32 v54, v54, v193
	v_mul_f32_e32 v55, v55, v193
	v_mul_f32_e32 v56, v56, v193
	v_mul_f32_e32 v57, v57, v193
	v_mul_f32_e32 v58, v58, v193
	v_mul_f32_e32 v59, v59, v193
	v_mul_f32_e32 v60, v60, v193
	v_mul_f32_e32 v61, v61, v193
	v_mul_f32_e32 v62, v62, v193
	v_mul_f32_e32 v63, v63, v193
	v_mul_f32_e32 v64, v64, v193
	v_mul_f32_e32 v65, v65, v193
	v_mul_f32_e32 v18, v18, v193
	v_mul_f32_e32 v19, v19, v193
	v_mul_f32_e32 v20, v20, v193
	v_mul_f32_e32 v21, v21, v193
	v_mul_f32_e32 v22, v22, v193
	v_mul_f32_e32 v23, v23, v193
	v_mul_f32_e32 v24, v24, v193
	v_mul_f32_e32 v25, v25, v193
	v_mul_f32_e32 v26, v26, v193
	v_mul_f32_e32 v27, v27, v193
	v_mul_f32_e32 v28, v28, v193
	v_mul_f32_e32 v29, v29, v193
	v_mul_f32_e32 v30, v30, v193
	v_mul_f32_e32 v31, v31, v193
	v_mul_f32_e32 v32, v32, v193
	v_mul_f32_e32 v33, v33, v193
	s_nop 1
	v_exp_f32_e32 v98, v98
	v_exp_f32_e32 v99, v99
	v_exp_f32_e32 v100, v100
	v_exp_f32_e32 v101, v101
	v_exp_f32_e32 v102, v102
	v_exp_f32_e32 v103, v103
	v_mov_b32_e32 v192, v98
	v_mov_b32_e32 v193, v99
	v_cvt_pk_bf16_f32 v98, v98, v99
	v_exp_f32_e32 v104, v104
	v_exp_f32_e32 v105, v105
	v_add_f32_e32 v192, v192, v100
	v_add_f32_e32 v193, v193, v101
	v_cvt_pk_bf16_f32 v99, v100, v101
	v_exp_f32_e32 v106, v106
	v_exp_f32_e32 v107, v107
	v_add_f32_e32 v192, v192, v102
	v_add_f32_e32 v193, v193, v103
	v_cvt_pk_bf16_f32 v100, v102, v103
	v_exp_f32_e32 v108, v108
	v_exp_f32_e32 v109, v109
	v_add_f32_e32 v192, v192, v104
	v_add_f32_e32 v193, v193, v105
	v_cvt_pk_bf16_f32 v101, v104, v105
	v_exp_f32_e32 v110, v110
	v_exp_f32_e32 v111, v111
	v_add_f32_e32 v192, v192, v106
	v_add_f32_e32 v193, v193, v107
	v_cvt_pk_bf16_f32 v102, v106, v107
	v_exp_f32_e32 v112, v112
	v_exp_f32_e32 v113, v113
	v_add_f32_e32 v192, v192, v108
	v_add_f32_e32 v193, v193, v109
	v_cvt_pk_bf16_f32 v103, v108, v109
	v_add_f32_e32 v192, v192, v110
	v_add_f32_e32 v193, v193, v111
	v_cvt_pk_bf16_f32 v104, v110, v111
	v_add_f32_e32 v192, v192, v112
	v_add_f32_e32 v193, v193, v113
	v_cvt_pk_bf16_f32 v105, v112, v113
	v_exp_f32_e32 v114, v114
	v_exp_f32_e32 v115, v115
	v_exp_f32_e32 v116, v116
	v_exp_f32_e32 v117, v117
	v_exp_f32_e32 v118, v118
	v_exp_f32_e32 v119, v119
	v_add_f32_e32 v192, v192, v114
	v_add_f32_e32 v193, v193, v115
	v_cvt_pk_bf16_f32 v114, v114, v115
	v_exp_f32_e32 v120, v120
	v_exp_f32_e32 v121, v121
	v_add_f32_e32 v192, v192, v116
	v_add_f32_e32 v193, v193, v117
	v_cvt_pk_bf16_f32 v115, v116, v117
	v_exp_f32_e32 v122, v122
	v_exp_f32_e32 v123, v123
	v_add_f32_e32 v192, v192, v118
	v_add_f32_e32 v193, v193, v119
	v_cvt_pk_bf16_f32 v116, v118, v119
	v_exp_f32_e32 v124, v124
	v_exp_f32_e32 v125, v125
	v_add_f32_e32 v192, v192, v120
	v_add_f32_e32 v193, v193, v121
	v_cvt_pk_bf16_f32 v117, v120, v121
	v_exp_f32_e32 v126, v126
	v_exp_f32_e32 v127, v127
	v_add_f32_e32 v192, v192, v122
	v_add_f32_e32 v193, v193, v123
	v_cvt_pk_bf16_f32 v118, v122, v123
	v_exp_f32_e32 v128, v128
	v_exp_f32_e32 v129, v129
	v_add_f32_e32 v192, v192, v124
	v_add_f32_e32 v193, v193, v125
	v_cvt_pk_bf16_f32 v119, v124, v125
	v_add_f32_e32 v192, v192, v126
	v_add_f32_e32 v193, v193, v127
	v_cvt_pk_bf16_f32 v120, v126, v127
	v_add_f32_e32 v192, v192, v128
	v_add_f32_e32 v193, v193, v129
	v_cvt_pk_bf16_f32 v121, v128, v129
	v_add_f32_e32 v192, v192, v193
	s_nop 4
	s_branch .Lbt_ok_b_x
; #define LAS __attribute__((address_space(3)))
; DI unsigned cvtpk(float lo, float hi) { f32x2 v = {lo, hi}; bf16x2_t b = __builtin_convertvector(v, bf16x2_t); return __builtin_bit_cast(unsigned, b); }
; DI float fexp2(float x) { return __builtin_amdgcn_exp2f(x); }
; DI float max2f(float a, float b) { float r; asm("v_max_f32_e32 %0, %1, %2" : "=v"(r) : "v"(a), "v"(b)); return r; }
; DI float xhalf_max(float v) { auto rr = __builtin_amdgcn_permlane32_swap(__float_as_uint(v), __float_as_uint(v), false, false); return max2f(__uint_as_float(rr[0]), __uint_as_float(rr[1])); }
; DI void attn_diff_unit(int ub, int Ssh, float lam, float post, const float* subg, const bf16_t* PROJ, bf16_t* O, LAS unsigned char* lds, int wid, int lane) {
;     ...
;         qk64<2, 0>(pa0, pa1, cur, qr, r32, hi);
;         qk64<2, 2>(pb0, pb1, cur, qr, r32, hi);
;         const float mxA = xhalf_max(rowmax32(pa0, pa1)), mxB = xhalf_max(rowmax32(pb0, pb1));
;         if (t == 0 || __any(mxA > mA + 8.0f || mxB > mB + 8.0f)) {
;             const float nA = (t == 0) ? mxA : max2f(mA, mxA), nB = (t == 0) ? mxB : max2f(mB, mxB);
;             const float fA = fexp2(mA - nA), fB = fexp2(mB - nB); mA = nA; mB = nB; lA *= fA; lB *= fB;
; #pragma unroll
;             for (int r = 0; r < 16; ++r) { a0[r] *= fA; a1[r] *= fA; b0[r] *= fB; b1[r] *= fB; }
;         }
;         float sA = 0.f, sB = 0.f;
; #pragma unroll
;         for (int r = 0; r < 16; ++r) { pa0[r] = fexp2(pa0[r] - mA); pa1[r] = fexp2(pa1[r] - mA); sA += pa0[r] + pa1[r]; }
;         pwA[0] = (u32x4){cvtpk(pa0[0], pa0[1]), cvtpk(pa0[2], pa0[3]), cvtpk(pa0[4], pa0[5]), cvtpk(pa0[6], pa0[7])};
;         pwA[1] = (u32x4){cvtpk(pa0[8], pa0[9]), cvtpk(pa0[10], pa0[11]), cvtpk(pa0[12], pa0[13]), cvtpk(pa0[14], pa0[15])};
;         pwA[2] = (u32x4){cvtpk(pa1[0], pa1[1]), cvtpk(pa1[2], pa1[3]), cvtpk(pa1[4], pa1[5]), cvtpk(pa1[6], pa1[7])};
;         pwA[3] = (u32x4){cvtpk(pa1[8], pa1[9]), cvtpk(pa1[10], pa1[11]), cvtpk(pa1[12], pa1[13]), cvtpk(pa1[14], pa1[15])};
;         LAS const unsigned char* vp = cur + 8192 + vlane;
; #pragma unroll
;         for (int ks = 0; ks < 4; ++ks) {
;             const s16x4 lo0 = vtr(vp + ks * 1024), hi0 = vtr(vp + ks * 1024 + 512), lo1 = vtr(vp + 4096 + ks * 1024), hi1 = vtr(vp + 4096 + ks * 1024 + 512);
.Lbt_redo_a_y:
	v_xor_b32_e32 v0, 0x4000, v168
	v_xor_b32_e32 v207, 0x4000, v169
	ds_read_b128 v[82:85], v0
	ds_read_b128 v[86:89], v207
	ds_read_b128 v[160:163], v0 offset:512
	ds_read_b128 v[164:167], v207 offset:512
	s_waitcnt lgkmcnt(0)
	v_mfma_f32_32x32x16_bf16 v[66:81], v[82:85], v[130:133], v[176:191]
	v_mfma_f32_32x32x16_bf16 v[66:81], v[86:89], v[134:137], v[66:81]
	v_mfma_f32_32x32x16_bf16 v[82:97], v[160:163], v[130:133], v[176:191]
	v_mfma_f32_32x32x16_bf16 v[82:97], v[164:167], v[134:137], v[82:97]
	s_nop 7
	s_nop 7
	v_max3_f32 v196, v66, v67, v68
	v_max3_f32 v197, v69, v70, v71
	v_max3_f32 v196, v196, v72, v73
	v_max3_f32 v197, v197, v74, v75
	v_max3_f32 v196, v196, v76, v77
	v_max3_f32 v197, v197, v78, v79
	v_max3_f32 v196, v196, v80, v81
	v_max3_f32 v197, v197, v82, v83
	v_max3_f32 v196, v196, v84, v85
	v_max3_f32 v197, v197, v86, v87
	v_max3_f32 v196, v196, v88, v89
	v_max3_f32 v197, v197, v90, v91
	v_max3_f32 v196, v196, v92, v93
	v_max3_f32 v197, v197, v94, v95
	v_max3_f32 v196, v196, v96, v97
	v_max_f32_e32 v196, v196, v197
	v_mov_b32_e32 v197, v196
	s_nop 1
	v_permlane32_swap_b32_e32 v196, v197
	v_max_f32_e32 v196, v196, v197
	v_max_f32_e32 v196, 0, v196
	v_exp_f32_e64 v197, -v196
	v_sub_f32_e32 v176, v176, v196
	v_sub_f32_e32 v177, v177, v196
	v_sub_f32_e32 v178, v178, v196
	v_sub_f32_e32 v179, v179, v196
	v_sub_f32_e32 v180, v180, v196
	v_sub_f32_e32 v181, v181, v196
	v_sub_f32_e32 v182, v182, v196
	v_sub_f32_e32 v183, v183, v196
	v_sub_f32_e32 v184, v184, v196
	v_sub_f32_e32 v185, v185, v196
	v_sub_f32_e32 v186, v186, v196
	v_sub_f32_e32 v187, v187, v196
	v_sub_f32_e32 v188, v188, v196
	v_sub_f32_e32 v189, v189, v196
	v_sub_f32_e32 v190, v190, v196
	v_sub_f32_e32 v191, v191, v196
	v_sub_f32_e32 v66, v66, v196
	v_sub_f32_e32 v67, v67, v196
	v_sub_f32_e32 v68, v68, v196
	v_sub_f32_e32 v69, v69, v196
	v_sub_f32_e32 v70, v70, v196
	v_sub_f32_e32 v71, v71, v196
	v_sub_f32_e32 v72, v72, v196
	v_sub_f32_e32 v73, v73, v196
	v_sub_f32_e32 v74, v74, v196
	v_sub_f32_e32 v75, v75, v196
	v_sub_f32_e32 v76, v76, v196
	v_sub_f32_e32 v77, v77, v196
	v_sub_f32_e32 v78, v78, v196
	v_sub_f32_e32 v79, v79, v196
	v_sub_f32_e32 v80, v80, v196
	v_sub_f32_e32 v81, v81, v196
	v_sub_f32_e32 v82, v82, v196
	v_sub_f32_e32 v83, v83, v196
	v_sub_f32_e32 v84, v84, v196
	v_sub_f32_e32 v85, v85, v196
	v_sub_f32_e32 v86, v86, v196
	v_sub_f32_e32 v87, v87, v196
	v_sub_f32_e32 v88, v88, v196
	v_sub_f32_e32 v89, v89, v196
	v_sub_f32_e32 v90, v90, v196
	v_sub_f32_e32 v91, v91, v196
	v_sub_f32_e32 v92, v92, v196
	v_sub_f32_e32 v93, v93, v196
	v_sub_f32_e32 v94, v94, v196
	v_sub_f32_e32 v95, v95, v196
	v_sub_f32_e32 v96, v96, v196
	v_sub_f32_e32 v97, v97, v196
	v_mul_f32_e32 v156, v156, v197
	v_mul_f32_e32 v34, v34, v197
	v_mul_f32_e32 v35, v35, v197
	v_mul_f32_e32 v36, v36, v197
	v_mul_f32_e32 v37, v37, v197
	v_mul_f32_e32 v38, v38, v197
	v_mul_f32_e32 v39, v39, v197
	v_mul_f32_e32 v40, v40, v197
	v_mul_f32_e32 v41, v41, v197
	v_mul_f32_e32 v42, v42, v197
	v_mul_f32_e32 v43, v43, v197
	v_mul_f32_e32 v44, v44, v197
	v_mul_f32_e32 v45, v45, v197
	v_mul_f32_e32 v46, v46, v197
	v_mul_f32_e32 v47, v47, v197
	v_mul_f32_e32 v48, v48, v197
	v_mul_f32_e32 v49, v49, v197
	v_mul_f32_e32 v2, v2, v197
	v_mul_f32_e32 v3, v3, v197
	v_mul_f32_e32 v4, v4, v197
	v_mul_f32_e32 v5, v5, v197
	v_mul_f32_e32 v6, v6, v197
	v_mul_f32_e32 v7, v7, v197
	v_mul_f32_e32 v8, v8, v197
	v_mul_f32_e32 v9, v9, v197
	v_mul_f32_e32 v10, v10, v197
	v_mul_f32_e32 v11, v11, v197
	v_mul_f32_e32 v12, v12, v197
	v_mul_f32_e32 v13, v13, v197
	v_mul_f32_e32 v14, v14, v197
	v_mul_f32_e32 v15, v15, v197
	v_mul_f32_e32 v16, v16, v197
	v_mul_f32_e32 v17, v17, v197
	s_nop 1
	v_exp_f32_e32 v66, v66
	v_exp_f32_e32 v67, v67
	v_exp_f32_e32 v68, v68
	v_exp_f32_e32 v69, v69
	v_exp_f32_e32 v70, v70
	v_exp_f32_e32 v71, v71
	v_mov_b32_e32 v196, v66
	v_mov_b32_e32 v197, v67
	v_cvt_pk_bf16_f32 v66, v66, v67
	v_exp_f32_e32 v72, v72
	v_exp_f32_e32 v73, v73
	v_add_f32_e32 v196, v196, v68
	v_add_f32_e32 v197, v197, v69
	v_cvt_pk_bf16_f32 v67, v68, v69
	v_exp_f32_e32 v74, v74
	v_exp_f32_e32 v75, v75
	v_add_f32_e32 v196, v196, v70
	v_add_f32_e32 v197, v197, v71
	v_cvt_pk_bf16_f32 v68, v70, v71
	v_exp_f32_e32 v76, v76
	v_exp_f32_e32 v77, v77
	v_add_f32_e32 v196, v196, v72
	v_add_f32_e32 v197, v197, v73
	v_cvt_pk_bf16_f32 v69, v72, v73
	v_exp_f32_e32 v78, v78
	v_exp_f32_e32 v79, v79
	v_add_f32_e32 v196, v196, v74
	v_add_f32_e32 v197, v197, v75
	v_cvt_pk_bf16_f32 v70, v74, v75
	v_exp_f32_e32 v80, v80
	v_exp_f32_e32 v81, v81
	v_add_f32_e32 v196, v196, v76
	v_add_f32_e32 v197, v197, v77
	v_cvt_pk_bf16_f32 v71, v76, v77
	v_add_f32_e32 v196, v196, v78
	v_add_f32_e32 v197, v197, v79
	v_cvt_pk_bf16_f32 v72, v78, v79
	v_add_f32_e32 v196, v196, v80
	v_add_f32_e32 v197, v197, v81
	v_cvt_pk_bf16_f32 v73, v80, v81
	v_exp_f32_e32 v82, v82
	v_exp_f32_e32 v83, v83
	v_exp_f32_e32 v84, v84
	v_exp_f32_e32 v85, v85
	v_exp_f32_e32 v86, v86
	v_exp_f32_e32 v87, v87
	v_add_f32_e32 v196, v196, v82
	v_add_f32_e32 v197, v197, v83
	v_cvt_pk_bf16_f32 v82, v82, v83
	v_exp_f32_e32 v88, v88
	v_exp_f32_e32 v89, v89
	v_add_f32_e32 v196, v196, v84
	v_add_f32_e32 v197, v197, v85
	v_cvt_pk_bf16_f32 v83, v84, v85
	v_exp_f32_e32 v90, v90
	v_exp_f32_e32 v91, v91
	v_add_f32_e32 v196, v196, v86
	v_add_f32_e32 v197, v197, v87
	v_cvt_pk_bf16_f32 v84, v86, v87
	v_exp_f32_e32 v92, v92
	v_exp_f32_e32 v93, v93
	v_add_f32_e32 v196, v196, v88
	v_add_f32_e32 v197, v197, v89
	v_cvt_pk_bf16_f32 v85, v88, v89
	v_exp_f32_e32 v94, v94
	v_exp_f32_e32 v95, v95
	v_add_f32_e32 v196, v196, v90
	v_add_f32_e32 v197, v197, v91
	v_cvt_pk_bf16_f32 v86, v90, v91
	v_exp_f32_e32 v96, v96
	v_exp_f32_e32 v97, v97
	v_add_f32_e32 v196, v196, v92
	v_add_f32_e32 v197, v197, v93
	v_cvt_pk_bf16_f32 v87, v92, v93
	v_add_f32_e32 v196, v196, v94
	v_add_f32_e32 v197, v197, v95
	v_cvt_pk_bf16_f32 v88, v94, v95
	v_add_f32_e32 v196, v196, v96
	v_add_f32_e32 v197, v197, v97
	v_cvt_pk_bf16_f32 v89, v96, v97
	v_add_f32_e32 v196, v196, v197
	ds_read_b64_tr_b16 v[74:75], v224 offset:8192
	ds_read_b64_tr_b16 v[76:77], v224 offset:8704
	ds_read_b64_tr_b16 v[78:79], v224 offset:12288
	ds_read_b64_tr_b16 v[80:81], v224 offset:12800
	ds_read_b64_tr_b16 v[90:91], v224 offset:9216
	ds_read_b64_tr_b16 v[92:93], v224 offset:9728
	ds_read_b64_tr_b16 v[94:95], v224 offset:13312
	ds_read_b64_tr_b16 v[96:97], v224 offset:13824
	s_nop 4
	s_branch .Lbt_ok_a_y
